# ssd_pass2 epilogue: all 16 group-norm weight loads early (13 at epilogue start, 3 after the transpose barrier), none left in the tail
# baseline (speedup 1.0000x reference)
.LBB0_220:
	s_waitcnt vmcnt(9)
	v_lshlrev_b32_e32 v248, 2, v166
	v_readlane_b32 s2, v254, 32
	v_readlane_b32 s3, v254, 33
	s_lshl_b32 s9, s17, 2
	s_add_u32 s2, s2, s9
	s_addc_u32 s3, s3, 0
	global_load_dwordx4 v[204:207], v248, s[2:3] offset:16
	global_load_dwordx4 v[208:211], v248, s[2:3]
	global_load_dwordx4 v[212:215], v248, s[2:3] offset:272
	global_load_dwordx4 v[216:219], v248, s[2:3] offset:256
	global_load_dwordx4 v[220:223], v248, s[2:3] offset:528
	global_load_dwordx4 v[224:227], v248, s[2:3] offset:512
	global_load_dwordx4 v[228:231], v248, s[2:3] offset:784
	global_load_dwordx4 v[232:235], v248, s[2:3] offset:768
	global_load_dwordx4 v[236:239], v248, s[2:3] offset:1040
	global_load_dwordx4 v[240:243], v248, s[2:3] offset:1024
	global_load_dwordx4 v[146:149], v248, s[2:3] offset:1296
	global_load_dwordx4 v[150:153], v248, s[2:3] offset:1280
	global_load_dwordx4 v[244:247], v248, s[2:3] offset:1552
	v_readlane_b32 s0, v251, 24
	v_add_u32_e32 v108, s19, v169
	v_ashrrev_i32_e32 v109, 31, v108
	v_lshlrev_b64 v[108:109], 12, v[108:109]
	v_readlane_b32 s1, v251, 25
	s_ashr_i32 s35, s34, 31
	v_readlane_b32 s40, v254, 20
	s_lshl_b32 s28, s17, 1
	s_lshl_b64 s[0:1], s[34:35], 2
	v_readlane_b32 s50, v254, 30
	v_mov_b32_e32 v133, v157
	v_readlane_b32 s51, v254, 31
	s_add_u32 s0, s50, s0
	s_addc_u32 s1, s51, s1
	v_cmp_lt_i32_e32 vcc, v188, v187
	v_mov_b32_e32 v110, v160
	v_readlane_b32 s0, v253, 62
	s_mov_b32 s56, 0x800000
	v_readlane_b32 s52, v254, 32
	v_add3_u32 v112, s0, v173, v137
	ds_read2_b64 v[104:107], v112 offset1:4
	v_add_u32_e32 v113, 0x1000, v112
	v_add_u32_e32 v118, 0x1800, v112
	s_lshl_b32 s0, s20, 2
	s_add_i32 s0, s0, 16
	s_waitcnt lgkmcnt(0)
	v_lshlrev_b32_e32 v32, 16, v104
	v_readlane_b32 s53, v254, 33
	v_readlane_b32 s8, v251, 51
	v_readlane_b32 s9, v251, 52
	v_readlane_b32 s72, v254, 41
	v_readlane_b32 s54, v254, 34
	v_readlane_b32 s55, v254, 35
	v_readlane_b32 s70, v254, 39
	v_readlane_b32 s73, v254, 42
	v_readlane_b32 s74, v254, 44
	v_readlane_b32 s76, v254, 46
	v_readlane_b32 s78, v254, 48
	v_readlane_b32 s82, v254, 52
	v_readlane_b32 s60, v254, 54
	v_readlane_b32 s62, v254, 56
	v_readlane_b32 s64, v254, 58
	v_readlane_b32 s66, v254, 60
	s_movk_i32 s68, 0x2040
	v_readlane_b32 s57, v254, 36
	v_readlane_b32 s58, v254, 37
	v_readlane_b32 s59, v254, 38
	v_readlane_b32 s71, v254, 40
	v_readlane_b32 s69, v254, 43
	v_readlane_b32 s75, v254, 45
	v_readlane_b32 s77, v254, 47
	v_readlane_b32 s79, v254, 49
	v_readlane_b32 s80, v254, 50
	v_readlane_b32 s81, v254, 51
	v_readlane_b32 s83, v254, 53
	v_readlane_b32 s61, v254, 55
	v_readlane_b32 s63, v254, 57
	v_readlane_b32 s65, v254, 59
	v_readlane_b32 s67, v254, 61
	s_movk_i32 s73, 0xf5
	s_movk_i32 s55, 0xfff
	s_mov_b32 s54, 0xf0c0
	v_readlane_b32 s41, v254, 21
	v_readlane_b32 s42, v254, 22
	v_readlane_b32 s43, v254, 23
	v_readlane_b32 s44, v254, 24
	v_readlane_b32 s45, v254, 25
	v_readlane_b32 s46, v254, 26
	v_readlane_b32 s47, v254, 27
	v_readlane_b32 s48, v254, 28
	v_readlane_b32 s49, v254, 29
	v_fma_f32 v111, v110, v32, v40
	v_and_b32_e32 v32, 0xffff0000, v104
	v_fma_f32 v104, v110, v32, v41
	v_lshlrev_b32_e32 v32, 16, v105
	v_fma_f32 v42, v110, v32, v42
	v_and_b32_e32 v32, 0xffff0000, v105
	v_add_u32_e32 v105, 0x800, v112
	ds_read2_b64 v[34:37], v105 offset0:32 offset1:36
	ds_read2_b64 v[38:41], v113 offset0:64 offset1:68
	v_fmac_f32_e32 v43, v110, v32
	ds_read2_b64 v[114:117], v105 offset0:40 offset1:44
	s_waitcnt lgkmcnt(2)
	v_lshlrev_b32_e32 v32, 16, v34
	v_fma_f32 v48, v110, v32, v48
	v_and_b32_e32 v32, 0xffff0000, v34
	v_fma_f32 v49, v110, v32, v49
	v_lshlrev_b32_e32 v32, 16, v35
	v_fma_f32 v50, v110, v32, v50
	v_and_b32_e32 v32, 0xffff0000, v35
	v_fmac_f32_e32 v51, v110, v32
	s_waitcnt lgkmcnt(1)
	v_lshlrev_b32_e32 v32, 16, v38
	v_fma_f32 v44, v110, v32, v44
	v_and_b32_e32 v32, 0xffff0000, v38
	v_fma_f32 v38, v110, v32, v45
	v_lshlrev_b32_e32 v32, 16, v39
	v_fma_f32 v45, v110, v32, v46
	v_and_b32_e32 v32, 0xffff0000, v39
	v_fmac_f32_e32 v47, v110, v32
	ds_read2_b64 v[32:35], v118 offset0:96 offset1:100
	ds_read2_b64 v[118:121], v118 offset0:104 offset1:108
	s_waitcnt lgkmcnt(1)
	v_lshlrev_b32_e32 v46, 16, v33
	v_fma_f32 v46, v110, v46, v54
	v_and_b32_e32 v33, 0xffff0000, v33
	v_and_b32_e32 v54, 0xffff0000, v107
	v_lshlrev_b32_e32 v39, 16, v32
	v_fmac_f32_e32 v55, v110, v33
	v_lshlrev_b32_e32 v33, 16, v106
	v_fmac_f32_e32 v59, v110, v54
	v_lshlrev_b32_e32 v54, 16, v36
	v_and_b32_e32 v36, 0xffff0000, v36
	v_fma_f32 v39, v110, v39, v52
	v_fma_f32 v33, v110, v33, v56
	v_and_b32_e32 v52, 0xffff0000, v106
	v_fma_f32 v56, v110, v36, v61
	v_lshlrev_b32_e32 v36, 16, v37
	v_and_b32_e32 v32, 0xffff0000, v32
	v_fma_f32 v52, v110, v52, v57
	v_fma_f32 v57, v110, v36, v62
	v_and_b32_e32 v36, 0xffff0000, v37
	v_fma_f32 v32, v110, v32, v53
	v_lshlrev_b32_e32 v53, 16, v107
	v_fmac_f32_e32 v63, v110, v36
	v_lshlrev_b32_e32 v36, 16, v40
	v_fma_f32 v53, v110, v53, v58
	v_fma_f32 v58, v110, v36, v64
	v_and_b32_e32 v36, 0xffff0000, v40
	v_fma_f32 v40, v110, v36, v65
	v_lshlrev_b32_e32 v36, 16, v41
	v_fma_f32 v54, v110, v54, v60
	v_fma_f32 v60, v110, v36, v66
	v_and_b32_e32 v36, 0xffff0000, v41
	v_fmac_f32_e32 v67, v110, v36
	v_lshlrev_b32_e32 v36, 16, v34
	v_and_b32_e32 v34, 0xffff0000, v34
	v_fma_f32 v61, v110, v34, v81
	v_lshlrev_b32_e32 v34, 16, v35
	v_fma_f32 v62, v110, v34, v82
	v_and_b32_e32 v34, 0xffff0000, v35
	v_fma_f32 v41, v110, v36, v80
	v_fmac_f32_e32 v83, v110, v34
	ds_read2_b64 v[34:37], v112 offset0:8 offset1:12
	v_and_b32_e32 v66, 0xffff0000, v114
	v_fma_f32 v66, v110, v66, v73
	v_and_b32_e32 v73, 0xffff0000, v115
	v_and_b32_e32 v80, 0xffff0000, v116
	s_waitcnt lgkmcnt(0)
	v_lshlrev_b32_e32 v65, 16, v35
	v_fma_f32 v65, v110, v65, v78
	v_lshlrev_b32_e32 v78, 16, v37
	v_fma_f32 v78, v110, v78, v90
	v_and_b32_e32 v37, 0xffff0000, v37
	v_and_b32_e32 v90, 0xffff0000, v121
	v_and_b32_e32 v35, 0xffff0000, v35
	v_fmac_f32_e32 v91, v110, v37
	v_lshlrev_b32_e32 v37, 16, v116
	v_fmac_f32_e32 v103, v110, v90
	v_lshl_add_u32 v90, v171, 2, s0
	s_movk_i32 s0, 0x2040
	v_fmac_f32_e32 v79, v110, v35
	v_lshlrev_b32_e32 v35, 16, v114
	v_fma_f32 v37, v110, v37, v92
	v_mad_u32_u24 v92, v172, s0, v90
	v_fma_f32 v35, v110, v35, v72
	v_lshlrev_b32_e32 v72, 16, v115
	ds_read2_b64 v[112:115], v113 offset0:72 offset1:76
	s_waitcnt lgkmcnt(0)
	s_barrier
	ds_write2_b32 v92, v111, v48 offset1:16
	v_add_u32_e32 v48, 0x800, v92
	ds_write2_b32 v48, v104, v49 offset0:4 offset1:20
	v_add_u32_e32 v49, 0x1000, v92
	ds_write2_b32 v49, v42, v50 offset0:8 offset1:24
	v_add_u32_e32 v42, 0x1800, v92
	ds_write2_b32 v42, v43, v51 offset0:12 offset1:28
	ds_write2_b32 v92, v44, v39 offset0:32 offset1:48
	ds_write2_b32 v48, v38, v32 offset0:36 offset1:52
	ds_write2_b32 v49, v45, v46 offset0:40 offset1:56
	ds_write2_b32 v42, v47, v55 offset0:44 offset1:60
	v_add_u32_e32 v32, 0x8000, v92
	ds_write2_b32 v32, v33, v54 offset0:64 offset1:80
	v_add_u32_e32 v33, 0x8800, v92
	v_add_u32_e32 v38, 0x9000, v92
	v_add_u32_e32 v39, 0x9800, v92
	ds_write2_b32 v33, v52, v56 offset0:68 offset1:84
	ds_write2_b32 v38, v53, v57 offset0:72 offset1:88
	ds_write2_b32 v39, v59, v63 offset0:76 offset1:92
	ds_write2_b32 v32, v58, v41 offset0:96 offset1:112
	ds_write2_b32 v33, v40, v61 offset0:100 offset1:116
	ds_write2_b32 v38, v60, v62 offset0:104 offset1:120
	ds_write2_b32 v39, v67, v83 offset0:108 offset1:124
	v_mov_b32_e32 v32, 0x10200
	v_lshlrev_b32_e32 v64, 16, v34
	v_mad_u32_u24 v32, v172, s0, v32
	v_fma_f32 v64, v110, v64, v76
	v_add_u32_e32 v33, v90, v32
	ds_write_b32 v33, v64
	v_mov_b32_e32 v33, 0x10a10
	v_and_b32_e32 v34, 0xffff0000, v34
	v_mad_u32_u24 v33, v172, s0, v33
	v_fma_f32 v34, v110, v34, v77
	v_add_u32_e32 v38, v90, v33
	ds_write_b32 v38, v34
	v_mov_b32_e32 v34, 0x11220
	v_mad_u32_u24 v34, v172, s0, v34
	v_add_u32_e32 v38, v90, v34
	ds_write_b32 v38, v65
	v_mov_b32_e32 v38, 0x11a30
	v_mad_u32_u24 v38, v172, s0, v38
	v_fmac_f32_e32 v75, v110, v73
	v_lshlrev_b32_e32 v73, 16, v112
	v_fma_f32 v80, v110, v80, v93
	v_add_u32_e32 v93, 64, v90
	v_add_u32_e32 v39, v90, v38
	v_fma_f32 v68, v110, v73, v68
	v_and_b32_e32 v73, 0xffff0000, v112
	ds_write_b32 v39, v79
	v_add_u32_e32 v39, v93, v32
	v_fma_f32 v69, v110, v73, v69
	v_lshlrev_b32_e32 v73, 16, v113
	ds_write_b32 v39, v35
	v_add_u32_e32 v35, v93, v33
	v_fma_f32 v72, v110, v72, v74
	v_fma_f32 v70, v110, v73, v70
	v_and_b32_e32 v73, 0xffff0000, v113
	ds_write_b32 v35, v66
	v_add_u32_e32 v35, v93, v34
	v_fmac_f32_e32 v71, v110, v73
	v_lshlrev_b32_e32 v73, 16, v118
	v_add_u32_e32 v43, 0x80, v90
	v_add_u32_e32 v50, 0xc0, v90
	ds_write_b32 v35, v72
	v_add_u32_e32 v35, v93, v38
	v_fma_f32 v73, v110, v73, v84
	v_and_b32_e32 v74, 0xffff0000, v118
	ds_write_b32 v35, v75
	v_add_u32_e32 v35, v43, v32
	v_add_u32_e32 v32, v50, v32
	v_fma_f32 v74, v110, v74, v85
	v_lshlrev_b32_e32 v76, 16, v119
	ds_write_b32 v32, v73
	v_add_u32_e32 v32, v50, v33
	v_fma_f32 v76, v110, v76, v86
	v_and_b32_e32 v77, 0xffff0000, v119
	ds_write_b32 v32, v74
	v_add_u32_e32 v32, v50, v34
	v_fmac_f32_e32 v87, v110, v77
	ds_write_b32 v32, v76
	v_add_u32_e32 v32, v50, v38
	ds_write_b32 v32, v87
	v_mov_b32_e32 v32, 0x18300
	v_lshlrev_b32_e32 v77, 16, v36
	v_mad_u32_u24 v32, v172, s0, v32
	v_fma_f32 v77, v110, v77, v88
	ds_write_b32 v35, v68
	v_add_u32_e32 v35, v43, v33
	v_add_u32_e32 v33, v90, v32
	ds_write_b32 v33, v77
	v_mov_b32_e32 v33, 0x18b10
	v_and_b32_e32 v36, 0xffff0000, v36
	v_mad_u32_u24 v33, v172, s0, v33
	v_fma_f32 v36, v110, v36, v89
	ds_write_b32 v35, v69
	v_add_u32_e32 v35, v43, v34
	v_add_u32_e32 v34, v90, v33
	ds_write_b32 v34, v36
	v_mov_b32_e32 v34, 0x19320
	ds_write_b32 v35, v70
	v_add_u32_e32 v35, v43, v38
	v_mad_u32_u24 v34, v172, s0, v34
	ds_write_b32 v35, v71
	v_add_u32_e32 v35, v90, v34
	ds_write_b32 v35, v78
	v_mad_u32_u24 v35, v172, s0, v198
	v_add_u32_e32 v36, v90, v35
	ds_write_b32 v36, v91
	v_add_u32_e32 v36, v93, v32
	v_lshlrev_b32_e32 v81, 16, v117
	ds_write_b32 v36, v37
	v_add_u32_e32 v36, v93, v33
	v_fma_f32 v81, v110, v81, v94
	v_and_b32_e32 v82, 0xffff0000, v117
	v_and_b32_e32 v86, 0xffff0000, v115
	ds_write_b32 v36, v80
	v_add_u32_e32 v36, v93, v34
	v_fmac_f32_e32 v95, v110, v82
	v_fmac_f32_e32 v99, v110, v86
	v_lshlrev_b32_e32 v86, 16, v120
	ds_write_b32 v36, v81
	v_add_u32_e32 v36, v93, v35
	v_fma_f32 v86, v110, v86, v100
	v_and_b32_e32 v88, 0xffff0000, v120
	ds_write_b32 v36, v95
	v_add_u32_e32 v36, v43, v32
	v_add_u32_e32 v32, v50, v32
	v_lshlrev_b32_e32 v82, 16, v114
	v_fma_f32 v88, v110, v88, v101
	v_lshlrev_b32_e32 v89, 16, v121
	ds_write_b32 v32, v86
	v_add_u32_e32 v32, v50, v33
	v_fma_f32 v82, v110, v82, v96
	v_and_b32_e32 v84, 0xffff0000, v114
	v_fma_f32 v89, v110, v89, v102
	ds_write_b32 v32, v88
	v_add_u32_e32 v32, v50, v34
	v_fma_f32 v84, v110, v84, v97
	v_lshlrev_b32_e32 v85, 16, v115
	ds_write_b32 v36, v82
	v_add_u32_e32 v36, v43, v33
	ds_write_b32 v32, v89
	v_add_u32_e32 v32, v50, v35
	s_movk_i32 s0, 0x810
	v_fma_f32 v85, v110, v85, v98
	ds_write_b32 v36, v84
	v_add_u32_e32 v36, v43, v34
	ds_write_b32 v32, v103
	v_mul_lo_u32 v33, v169, s0
	v_lshlrev_b32_e32 v32, 2, v166
	ds_write_b32 v36, v85
	v_add_u32_e32 v36, v43, v35
	v_add3_u32 v76, 16, v33, v32
	ds_write_b32 v36, v99
	s_waitcnt lgkmcnt(0)
	s_barrier
	ds_read_b128 v[34:37], v76
	ds_read_b128 v[38:41], v76 offset:16
	s_waitcnt vmcnt(0)
	s_lshl_b32 s2, s17, 2
	s_add_u32 s2, s52, s2
	s_addc_u32 s3, s53, 0
	global_load_dwordx4 v[172:175], v32, s[2:3] offset:1536
	global_load_dwordx4 v[176:179], v32, s[2:3] offset:1808
	global_load_dwordx4 v[168:171], v32, s[2:3] offset:1792
	v_lshlrev_b32_e32 v33, 16, v28
	v_and_b32_e32 v28, 0xffff0000, v28
	v_lshlrev_b32_e32 v42, 16, v29
	s_waitcnt lgkmcnt(1)
	v_mul_f32_e32 v72, v35, v28
	v_mul_f32_e32 v73, v34, v33
	v_mul_f32_e32 v77, v72, v72
	v_and_b32_e32 v29, 0xffff0000, v29
	v_mul_f32_e32 v71, v36, v42
	v_fmac_f32_e32 v77, v73, v73
	v_lshlrev_b32_e32 v43, 16, v30
	v_and_b32_e32 v30, 0xffff0000, v30
	v_lshlrev_b32_e32 v44, 16, v31
	v_and_b32_e32 v31, 0xffff0000, v31
	v_mul_f32_e32 v70, v37, v29
	v_fmac_f32_e32 v77, v71, v71
	s_waitcnt lgkmcnt(0)
	v_mul_f32_e32 v69, v38, v43
	v_mul_f32_e32 v68, v39, v30
	v_mul_f32_e32 v65, v41, v31
	v_fmac_f32_e32 v77, v70, v70
	ds_read_b128 v[28:31], v76 offset:256
	ds_read_b128 v[34:37], v76 offset:272
	v_fmac_f32_e32 v77, v69, v69
	v_mul_f32_e32 v67, v40, v44
	v_fmac_f32_e32 v77, v68, v68
	v_fmac_f32_e32 v77, v67, v67
	v_lshlrev_b32_e32 v33, 16, v24
	v_fmac_f32_e32 v77, v65, v65
	v_and_b32_e32 v24, 0xffff0000, v24
	s_waitcnt lgkmcnt(1)
	v_mul_f32_e32 v66, v28, v33
	v_lshlrev_b32_e32 v38, 16, v25
	v_mul_f32_e32 v63, v29, v24
	v_fmac_f32_e32 v77, v66, v66
	v_and_b32_e32 v25, 0xffff0000, v25
	v_mul_f32_e32 v60, v30, v38
	v_fmac_f32_e32 v77, v63, v63
	v_lshlrev_b32_e32 v39, 16, v26
	v_and_b32_e32 v26, 0xffff0000, v26
	v_lshlrev_b32_e32 v40, 16, v27
	v_and_b32_e32 v27, 0xffff0000, v27
	v_mul_f32_e32 v56, v31, v25
	v_fmac_f32_e32 v77, v60, v60
	s_waitcnt lgkmcnt(0)
	v_mul_f32_e32 v51, v34, v39
	v_mul_f32_e32 v45, v35, v26
	v_mul_f32_e32 v35, v37, v27
	v_fmac_f32_e32 v77, v56, v56
	ds_read_b128 v[24:27], v76 offset:512
	ds_read_b128 v[28:31], v76 offset:528
	v_fmac_f32_e32 v77, v51, v51
	v_mul_f32_e32 v40, v36, v40
	v_fmac_f32_e32 v77, v45, v45
	v_fmac_f32_e32 v77, v40, v40
	v_lshlrev_b32_e32 v33, 16, v20
	v_fmac_f32_e32 v77, v35, v35
	v_and_b32_e32 v20, 0xffff0000, v20
	s_waitcnt lgkmcnt(1)
	v_mul_f32_e32 v64, v24, v33
	v_lshlrev_b32_e32 v34, 16, v21
	v_mul_f32_e32 v61, v25, v20
	v_fmac_f32_e32 v77, v64, v64
	v_and_b32_e32 v21, 0xffff0000, v21
	v_mul_f32_e32 v57, v26, v34
	v_fmac_f32_e32 v77, v61, v61
	v_lshlrev_b32_e32 v36, 16, v22
	v_and_b32_e32 v22, 0xffff0000, v22
	v_lshlrev_b32_e32 v37, 16, v23
	v_and_b32_e32 v23, 0xffff0000, v23
	v_mul_f32_e32 v52, v27, v21
	v_fmac_f32_e32 v77, v57, v57
	s_waitcnt lgkmcnt(0)
	v_mul_f32_e32 v46, v28, v36
	v_mul_f32_e32 v41, v29, v22
	v_mul_f32_e32 v36, v30, v37
	v_mul_f32_e32 v30, v31, v23
	v_fmac_f32_e32 v77, v52, v52
	ds_read_b128 v[20:23], v76 offset:768
	ds_read_b128 v[24:27], v76 offset:784
	v_fmac_f32_e32 v77, v46, v46
	v_fmac_f32_e32 v77, v41, v41
	v_fmac_f32_e32 v77, v36, v36
	v_lshlrev_b32_e32 v28, 16, v16
	v_fmac_f32_e32 v77, v30, v30
	v_and_b32_e32 v16, 0xffff0000, v16
	s_waitcnt lgkmcnt(1)
	v_mul_f32_e32 v62, v20, v28
	v_lshlrev_b32_e32 v29, 16, v17
	v_mul_f32_e32 v58, v21, v16
	v_fmac_f32_e32 v77, v62, v62
	v_and_b32_e32 v17, 0xffff0000, v17
	v_mul_f32_e32 v53, v22, v29
	v_fmac_f32_e32 v77, v58, v58
	v_lshlrev_b32_e32 v31, 16, v18
	v_and_b32_e32 v18, 0xffff0000, v18
	v_lshlrev_b32_e32 v33, 16, v19
	v_and_b32_e32 v19, 0xffff0000, v19
	v_mul_f32_e32 v47, v23, v17
	v_fmac_f32_e32 v77, v53, v53
	s_waitcnt lgkmcnt(0)
	v_mul_f32_e32 v42, v24, v31
	v_mul_f32_e32 v37, v25, v18
	v_mul_f32_e32 v27, v27, v19
	v_fmac_f32_e32 v77, v47, v47
	ds_read_b128 v[16:19], v76 offset:1024
	ds_read_b128 v[20:23], v76 offset:1040
	v_fmac_f32_e32 v77, v42, v42
	v_mul_f32_e32 v31, v26, v33
	v_fmac_f32_e32 v77, v37, v37
	v_fmac_f32_e32 v77, v31, v31
	v_lshlrev_b32_e32 v24, 16, v12
	v_fmac_f32_e32 v77, v27, v27
	v_and_b32_e32 v12, 0xffff0000, v12
	s_waitcnt lgkmcnt(1)
	v_mul_f32_e32 v59, v16, v24
	v_lshlrev_b32_e32 v25, 16, v13
	v_mul_f32_e32 v54, v17, v12
	v_fmac_f32_e32 v77, v59, v59
	v_and_b32_e32 v13, 0xffff0000, v13
	v_mul_f32_e32 v48, v18, v25
	v_fmac_f32_e32 v77, v54, v54
	v_lshlrev_b32_e32 v26, 16, v14
	v_and_b32_e32 v14, 0xffff0000, v14
	v_lshlrev_b32_e32 v28, 16, v15
	v_and_b32_e32 v15, 0xffff0000, v15
	v_mul_f32_e32 v43, v19, v13
	v_fmac_f32_e32 v77, v48, v48
	s_waitcnt lgkmcnt(0)
	v_mul_f32_e32 v38, v20, v26
	v_mul_f32_e32 v33, v21, v14
	v_mul_f32_e32 v24, v23, v15
	v_fmac_f32_e32 v77, v43, v43
	ds_read_b128 v[12:15], v76 offset:1280
	ds_read_b128 v[16:19], v76 offset:1296
	v_fmac_f32_e32 v77, v38, v38
	v_mul_f32_e32 v28, v22, v28
	v_fmac_f32_e32 v77, v33, v33
	v_fmac_f32_e32 v77, v28, v28
	v_lshlrev_b32_e32 v20, 16, v8
	v_fmac_f32_e32 v77, v24, v24
	v_and_b32_e32 v8, 0xffff0000, v8
	s_waitcnt lgkmcnt(1)
	v_mul_f32_e32 v55, v12, v20
	v_lshlrev_b32_e32 v21, 16, v9
	v_mul_f32_e32 v49, v13, v8
	v_fmac_f32_e32 v77, v55, v55
	v_and_b32_e32 v9, 0xffff0000, v9
	v_mul_f32_e32 v44, v14, v21
	v_fmac_f32_e32 v77, v49, v49
	v_lshlrev_b32_e32 v22, 16, v10
	v_and_b32_e32 v10, 0xffff0000, v10
	v_lshlrev_b32_e32 v23, 16, v11
	v_and_b32_e32 v11, 0xffff0000, v11
	v_mul_f32_e32 v39, v15, v9
	v_fmac_f32_e32 v77, v44, v44
	s_waitcnt lgkmcnt(0)
	v_mul_f32_e32 v34, v16, v22
	v_mul_f32_e32 v29, v17, v10
	v_mul_f32_e32 v25, v18, v23
	v_mul_f32_e32 v23, v19, v11
	v_fmac_f32_e32 v77, v39, v39
	ds_read_b128 v[8:11], v76 offset:1536
	ds_read_b128 v[12:15], v76 offset:1552
	v_fmac_f32_e32 v77, v34, v34
	v_fmac_f32_e32 v77, v29, v29
	v_fmac_f32_e32 v77, v25, v25
	v_lshlrev_b32_e32 v16, 16, v4
	v_fmac_f32_e32 v77, v23, v23
	v_and_b32_e32 v4, 0xffff0000, v4
	s_waitcnt lgkmcnt(1)
	v_mul_f32_e32 v50, v8, v16
	v_lshlrev_b32_e32 v17, 16, v5
	v_and_b32_e32 v5, 0xffff0000, v5
	v_lshlrev_b32_e32 v18, 16, v6
	v_and_b32_e32 v6, 0xffff0000, v6
	v_lshlrev_b32_e32 v74, 16, v7
	v_and_b32_e32 v7, 0xffff0000, v7
	v_mul_f32_e32 v26, v9, v4
	v_fmac_f32_e32 v77, v50, v50
	v_mul_f32_e32 v22, v10, v17
	v_mul_f32_e32 v21, v11, v5
	s_waitcnt lgkmcnt(0)
	v_mul_f32_e32 v20, v12, v18
	v_mul_f32_e32 v19, v13, v6
	v_mul_f32_e32 v18, v14, v74
	v_mul_f32_e32 v17, v15, v7
	v_fmac_f32_e32 v77, v26, v26
	v_lshlrev_b32_e32 v4, 16, v0
	v_and_b32_e32 v5, 0xffff0000, v0
	v_lshlrev_b32_e32 v6, 16, v1
	v_and_b32_e32 v7, 0xffff0000, v1
	v_lshlrev_b32_e32 v8, 16, v2
	v_and_b32_e32 v9, 0xffff0000, v2
	v_lshlrev_b32_e32 v74, 16, v3
	v_and_b32_e32 v75, 0xffff0000, v3
	ds_read_b128 v[0:3], v76 offset:1792
	v_fmac_f32_e32 v77, v22, v22
	v_fmac_f32_e32 v77, v21, v21
	v_fmac_f32_e32 v77, v20, v20
	v_fmac_f32_e32 v77, v19, v19
	v_fmac_f32_e32 v77, v18, v18
	s_waitcnt lgkmcnt(0)
	v_pk_mul_f32 v[14:15], v[0:1], v[4:5]
	v_fmac_f32_e32 v77, v17, v17
	v_pk_mul_f32 v[0:1], v[14:15], v[14:15]
	v_pk_mul_f32 v[12:13], v[2:3], v[6:7]
	v_add_f32_e32 v0, v77, v0
	v_add_f32_e32 v4, v0, v1
	v_pk_mul_f32 v[0:1], v[12:13], v[12:13]
	s_lshl_b32 s0, s17, 2
	v_add_f32_e32 v0, v4, v0
	v_add_f32_e32 v4, v0, v1
	ds_read_b128 v[0:3], v76 offset:1808
	s_add_u32 s0, s52, s0
	s_addc_u32 s1, s53, 0
	s_waitcnt lgkmcnt(0)
	v_pk_mul_f32 v[10:11], v[0:1], v[8:9]
	s_nop 0
	v_pk_mul_f32 v[0:1], v[10:11], v[10:11]
	v_pk_mul_f32 v[8:9], v[2:3], v[74:75]
	v_add_f32_e32 v0, v4, v0
	v_add_f32_e32 v4, v0, v1
	v_pk_mul_f32 v[0:1], v[8:9], v[8:9]
	s_nop 0
	v_add_f32_e32 v0, v4, v0
	v_add_f32_e32 v0, v0, v1
	v_cndmask_b32_e32 v1, v185, v188, vcc
	v_lshlrev_b32_e32 v1, 2, v1
	ds_bpermute_b32 v1, v1, v0
	v_cmp_lt_i32_e32 vcc, v189, v187
	s_waitcnt lgkmcnt(0)
	v_add_f32_e32 v0, v0, v1
	v_cndmask_b32_e32 v1, v185, v189, vcc
	v_lshlrev_b32_e32 v1, 2, v1
	ds_bpermute_b32 v1, v1, v0
	v_cmp_lt_i32_e32 vcc, v190, v187
	s_waitcnt lgkmcnt(0)
	v_add_f32_e32 v0, v0, v1
	v_cndmask_b32_e32 v1, v185, v190, vcc
	v_lshlrev_b32_e32 v1, 2, v1
	ds_bpermute_b32 v1, v1, v0
	s_waitcnt lgkmcnt(0)
	v_add_f32_e32 v0, v0, v1
	v_fmamk_f32 v0, v0, 0x3b000000, v182
	v_cmp_gt_f32_e32 vcc, s56, v0
	v_mul_f32_e32 v1, 0x4b800000, v0
	s_nop 0
	v_cndmask_b32_e32 v0, v0, v1, vcc
	v_rsq_f32_e32 v0, v0
	s_nop 0
	v_mul_f32_e32 v1, 0x45800000, v0
	v_cndmask_b32_e32 v16, v0, v1, vcc
	v_mul_f32_e32 v73, v73, v16
	v_mul_f32_e32 v69, v69, v16
	v_mul_f32_e32 v68, v68, v16
	v_mul_f32_e32 v67, v67, v16
	v_mul_f32_e32 v72, v72, v16
	v_mul_f32_e32 v71, v71, v16
	v_mul_f32_e32 v70, v70, v16
	v_mul_f32_e32 v51, v51, v16
	v_mul_f32_e32 v60, v60, v16
	v_mul_f32_e32 v56, v56, v16
	v_mul_f32_e32 v20, v20, v16
	v_mul_f32_e32 v22, v22, v16
	v_mul_f32_e32 v21, v21, v16
	v_mul_f32_e32 v10, v10, v16
	v_mul_f32_e32 v12, v12, v16
	v_mul_f32_e32 v13, v13, v16
	s_waitcnt vmcnt(15)
	v_mul_f32_e32 v0, v204, v69
	s_waitcnt vmcnt(14)
	v_mul_f32_e32 v4, v208, v73
	v_mul_f32_e32 v1, v205, v68
	v_mul_f32_e32 v67, v206, v67
	v_mul_f32_e32 v2, v65, v16
	v_mul_f32_e32 v5, v209, v72
	v_mul_f32_e32 v65, v207, v2
	v_cvt_pk_bf16_f32 v2, v4, v5
	v_cvt_pk_bf16_f32 v4, v0, v1
	v_lshl_add_u64 v[0:1], s[8:9], 0, v[108:109]
	v_lshl_add_u64 v[0:1], v[0:1], 0, s[28:29]
	v_lshl_add_u64 v[0:1], v[0:1], 0, v[132:133]
	v_mul_f32_e32 v6, v210, v71
	v_mul_f32_e32 v7, v211, v70
	v_cvt_pk_bf16_f32 v3, v6, v7
	v_cvt_pk_bf16_f32 v5, v67, v65
	global_store_dwordx4 v[0:1], v[2:5], off
	v_mul_f32_e32 v6, v66, v16
	v_mul_f32_e32 v7, v63, v16
	s_waitcnt vmcnt(14)
	v_mul_f32_e32 v51, v51, v212
	v_mul_f32_e32 v2, v45, v16
	v_mul_f32_e32 v45, v2, v213
	v_mul_f32_e32 v2, v40, v16
	v_mul_f32_e32 v40, v2, v214
	v_mul_f32_e32 v2, v35, v16
	v_mul_f32_e32 v5, v2, v215
	s_waitcnt vmcnt(13)
	v_mul_f32_e32 v6, v6, v216
	v_mul_f32_e32 v7, v7, v217
	v_mul_f32_e32 v60, v60, v218
	v_mul_f32_e32 v56, v56, v219
	v_cvt_pk_bf16_f32 v2, v6, v7
	v_cvt_pk_bf16_f32 v3, v60, v56
	v_cvt_pk_bf16_f32 v4, v51, v45
	v_cvt_pk_bf16_f32 v5, v40, v5
	global_store_dwordx4 v[0:1], v[2:5], off offset:128
	v_mul_f32_e32 v45, v46, v16
	v_mul_f32_e32 v6, v64, v16
	v_mul_f32_e32 v7, v61, v16
	v_mul_f32_e32 v35, v57, v16
	v_mul_f32_e32 v40, v52, v16
	s_waitcnt vmcnt(13)
	v_mul_f32_e32 v45, v45, v220
	v_mul_f32_e32 v2, v41, v16
	v_mul_f32_e32 v41, v2, v221
	v_mul_f32_e32 v2, v36, v16
	v_mul_f32_e32 v36, v2, v222
	v_mul_f32_e32 v2, v30, v16
	v_mul_f32_e32 v5, v2, v223
	s_waitcnt vmcnt(12)
	v_mul_f32_e32 v6, v6, v224
	v_mul_f32_e32 v7, v7, v225
	v_mul_f32_e32 v35, v35, v226
	v_mul_f32_e32 v40, v40, v227
	v_cvt_pk_bf16_f32 v2, v6, v7
	v_cvt_pk_bf16_f32 v3, v35, v40
	v_cvt_pk_bf16_f32 v4, v45, v41
	v_cvt_pk_bf16_f32 v5, v36, v5
	global_store_dwordx4 v[0:1], v[2:5], off offset:256
	v_mul_f32_e32 v36, v42, v16
	v_mul_f32_e32 v6, v62, v16
	v_mul_f32_e32 v7, v58, v16
	v_mul_f32_e32 v30, v53, v16
	v_mul_f32_e32 v35, v47, v16
	s_waitcnt vmcnt(12)
	v_mul_f32_e32 v36, v36, v228
	v_mul_f32_e32 v2, v37, v16
	v_mul_f32_e32 v37, v2, v229
	v_mul_f32_e32 v2, v31, v16
	v_mul_f32_e32 v31, v2, v230
	v_mul_f32_e32 v2, v27, v16
	v_mul_f32_e32 v5, v2, v231
	s_waitcnt vmcnt(11)
	v_mul_f32_e32 v6, v6, v232
	v_mul_f32_e32 v7, v7, v233
	v_mul_f32_e32 v30, v30, v234
	v_mul_f32_e32 v35, v35, v235
	v_cvt_pk_bf16_f32 v2, v6, v7
	v_cvt_pk_bf16_f32 v3, v30, v35
	v_cvt_pk_bf16_f32 v4, v36, v37
	v_cvt_pk_bf16_f32 v5, v31, v5
	global_store_dwordx4 v[0:1], v[2:5], off offset:384
	v_mul_f32_e32 v31, v38, v16
	v_mul_f32_e32 v6, v59, v16
	v_mul_f32_e32 v7, v54, v16
	v_mul_f32_e32 v27, v48, v16
	v_mul_f32_e32 v30, v43, v16
	s_waitcnt vmcnt(11)
	v_mul_f32_e32 v31, v31, v236
	v_mul_f32_e32 v2, v33, v16
	v_mul_f32_e32 v33, v2, v237
	v_mul_f32_e32 v2, v28, v16
	v_mul_f32_e32 v28, v2, v238
	v_mul_f32_e32 v2, v24, v16
	v_mul_f32_e32 v5, v2, v239
	s_waitcnt vmcnt(10)
	v_mul_f32_e32 v6, v6, v240
	v_mul_f32_e32 v7, v7, v241
	v_mul_f32_e32 v27, v27, v242
	v_mul_f32_e32 v30, v30, v243
	v_cvt_pk_bf16_f32 v2, v6, v7
	v_cvt_pk_bf16_f32 v3, v27, v30
	v_cvt_pk_bf16_f32 v4, v31, v33
	v_cvt_pk_bf16_f32 v5, v28, v5
	global_store_dwordx4 v[0:1], v[2:5], off offset:512
	v_mul_f32_e32 v28, v34, v16
	v_mul_f32_e32 v6, v55, v16
	v_mul_f32_e32 v7, v49, v16
	v_mul_f32_e32 v24, v44, v16
	v_mul_f32_e32 v27, v39, v16
	s_waitcnt vmcnt(10)
	v_mul_f32_e32 v28, v28, v146
	v_mul_f32_e32 v2, v29, v16
	v_mul_f32_e32 v29, v2, v147
	v_mul_f32_e32 v2, v25, v16
	v_mul_f32_e32 v25, v2, v148
	v_mul_f32_e32 v2, v23, v16
	v_mul_f32_e32 v5, v2, v149
	s_waitcnt vmcnt(9)
	v_mul_f32_e32 v6, v6, v150
	v_mul_f32_e32 v7, v7, v151
	v_mul_f32_e32 v24, v24, v152
	v_mul_f32_e32 v27, v27, v153
	v_cvt_pk_bf16_f32 v2, v6, v7
	v_cvt_pk_bf16_f32 v3, v24, v27
	v_cvt_pk_bf16_f32 v4, v28, v29
	v_cvt_pk_bf16_f32 v5, v25, v5
	global_store_dwordx4 v[0:1], v[2:5], off offset:640
	v_mul_f32_e32 v6, v50, v16
	v_mul_f32_e32 v7, v26, v16
	s_waitcnt vmcnt(9)
	v_mul_f32_e32 v20, v20, v244
	v_mul_f32_e32 v2, v19, v16
	v_mul_f32_e32 v19, v2, v245
	v_mul_f32_e32 v2, v18, v16
	v_mul_f32_e32 v18, v2, v246
	v_mul_f32_e32 v2, v17, v16
	v_mul_f32_e32 v5, v2, v247
	s_waitcnt vmcnt(8)
	v_mul_f32_e32 v6, v6, v172
	v_mul_f32_e32 v7, v7, v173
	v_mul_f32_e32 v22, v22, v174
	v_mul_f32_e32 v21, v21, v175
	v_cvt_pk_bf16_f32 v2, v6, v7
	v_cvt_pk_bf16_f32 v3, v22, v21
	v_cvt_pk_bf16_f32 v4, v20, v19
	v_cvt_pk_bf16_f32 v5, v18, v5
	global_store_dwordx4 v[0:1], v[2:5], off offset:768
	v_mul_f32_e32 v6, v14, v16
	v_mul_f32_e32 v7, v15, v16
	s_mov_b64 s[0:1], 0
	s_waitcnt vmcnt(8)
	v_mul_f32_e32 v10, v10, v176
	v_mul_f32_e32 v2, v11, v16
	v_mul_f32_e32 v11, v2, v177
	v_mul_f32_e32 v2, v8, v16
	v_mul_f32_e32 v8, v2, v178
	v_mul_f32_e32 v2, v9, v16
	v_mul_f32_e32 v5, v2, v179
	s_waitcnt vmcnt(7)
	v_mul_f32_e32 v6, v6, v168
	v_mul_f32_e32 v7, v7, v169
	v_mul_f32_e32 v12, v12, v170
	v_mul_f32_e32 v13, v13, v171
	v_cvt_pk_bf16_f32 v2, v6, v7
	v_cvt_pk_bf16_f32 v3, v12, v13
	v_cvt_pk_bf16_f32 v4, v10, v11
	v_cvt_pk_bf16_f32 v5, v8, v5
	global_store_dwordx4 v[0:1], v[2:5], off offset:896
	s_barrier
